# sample differential-attention tile loop: f32-to-bf16 K/V conversion with v_cvt_pk_bf16_f32 (RNE, same kind the baseline already uses) instead of the 6-instruction integer bit trick
# baseline (speedup 1.0000x reference)
; #define LAS __attribute__((address_space(3)))
; __device__ __forceinline__ unsigned pk2(float lo, float hi) { return f2bf(lo) | (f2bf(hi) << 16); }
; template <bool DIFF, bool FIXED, bool F32SRC> ...
;     ...
;         if (F32SRC) {
; #pragma unroll
;             for (int i = 0; i < NCH; ++i) {
;                 const int c = tid + 512 * i, row = c / (HW / 8), ch = c % (HW / 8);
;                 const size_t so = (j == u.jhi) ? (size_t)min(row, 15) * PITCH + u.h * HW + ch * 8 : (size_t)(64 * j + row) * PITCH + u.h * HW + ch * 8;
;                 const float* ks_ = ((j == u.jhi) ? kn : kc) + so; const float* vs_ = ((j == u.jhi) ? vn : vc) + so;
;                 const f32x4 k0 = ((const f32x4*)ks_)[0], k1 = ((const f32x4*)ks_)[1], v0 = ((const f32x4*)vs_)[0], v1 = ((const f32x4*)vs_)[1];
;                 u32x4 kw, vw; kw.x = pk2(k0.x, k0.y); kw.y = pk2(k0.z, k0.w); kw.z = pk2(k1.x, k1.y); kw.w = pk2(k1.z, k1.w); vw.x = pk2(v0.x, v0.y); vw.y = pk2(v0.z, v0.w); vw.z = pk2(v1.x, v1.y); vw.w = pk2(v1.z, v1.w);
;                 *(LAS u32x4*)(lds + buf * BUF + row * RB + ((ch ^ (DIFF ? (row & 15) : ((row >> 1) & 7))) << 4)) = kw;
;                 *(LAS u32x4*)(lds + buf * BUF + KBUF + (row >> 3) * (NDB * 512) + (ch >> 2) * 512 + (row & 7) * 64 + (ch & 3) * 16) = vw;
;             }
;             __syncthreads();
;         } else {
;         const int b2 = (buf >= 1) ? buf - 1 : 2;
;         if (j - 2 >= u.jlo) ATT_DMA(j - 2, b2);
;         }
;         const bool comp = (wact && j <= cq && j >= cq - win);
;         if (comp) {
;             const LAS unsigned char* kb = lds + buf * BUF; const LAS unsigned char* vb = kb + KBUF;
;             const int dqi = qloc - 64 * j - 4 * hi; const float dq = (float)dqi;
;             bf16x8 kf0[2], kf1[2];
; #pragma unroll
;             for (int ks = 0; ks < 2; ++ks) { kf0[ks] = *(const LAS bf16x8*)(kb + koff[ks]); kf1[ks] = *(const LAS bf16x8*)(kb + koff[ks] + 32 * RB); }
.LBB0_447:
	s_lshl_b32 s0, s59, 15
	s_add_i32 s64, s0, 0
	s_cmpk_eq_i32 s60, 0x800
	s_cselect_b64 vcc, -1, 0
	v_add_u32_e32 v0, s60, v222
	v_cndmask_b32_e32 v66, v0, v223, vcc
	v_ashrrev_i32_e32 v67, 31, v66
	v_lshlrev_b64 v[66:67], 10, v[66:67]
	s_and_b64 s[0:1], vcc, exec
	v_lshl_add_u64 v[66:67], v[134:135], 0, v[66:67]
	s_cselect_b32 s1, s58, s29
	s_cselect_b32 s0, s51, s28
	s_cselect_b32 s17, s50, s25
	s_cselect_b32 s16, s30, s24
	v_lshlrev_b64 v[66:67], 2, v[66:67]
	v_lshl_add_u64 v[70:71], s[16:17], 0, v[66:67]
	v_lshl_add_u64 v[78:79], s[0:1], 0, v[66:67]
	global_load_dwordx4 v[66:69], v[70:71], off offset:16
	s_nop 0
	global_load_dwordx4 v[70:73], v[70:71], off
	s_nop 0
	global_load_dwordx4 v[74:77], v[78:79], off offset:16
	s_nop 0
	global_load_dwordx4 v[78:81], v[78:79], off
	v_add_u32_e32 v114, s60, v230
	v_cndmask_b32_e32 v114, v114, v231, vcc
	v_ashrrev_i32_e32 v115, 31, v114
	v_lshlrev_b64 v[114:115], 10, v[114:115]
	v_lshl_add_u64 v[114:115], v[136:137], 0, v[114:115]
	v_lshlrev_b64 v[114:115], 2, v[114:115]
	v_lshl_add_u64 v[116:117], s[16:17], 0, v[114:115]
	v_lshl_add_u64 v[118:119], s[0:1], 0, v[114:115]
	global_load_dwordx4 v[82:85], v[116:117], off offset:16
	global_load_dwordx4 v[86:89], v[116:117], off
	global_load_dwordx4 v[90:93], v[118:119], off offset:16
	global_load_dwordx4 v[94:97], v[118:119], off
	s_cmp_le_i32 s61, s62
	s_waitcnt vmcnt(4)
	v_cvt_pk_bf16_f32 v70, v70, v71
	v_cvt_pk_bf16_f32 v71, v72, v73
	v_cvt_pk_bf16_f32 v72, v66, v67
	v_cvt_pk_bf16_f32 v73, v68, v69
	v_cvt_pk_bf16_f32 v66, v78, v79
	v_cvt_pk_bf16_f32 v67, v80, v81
	v_cvt_pk_bf16_f32 v68, v74, v75
	v_cvt_pk_bf16_f32 v69, v76, v77
	v_add3_u32 v0, s64, v224, v225
	ds_write_b128 v0, v[70:73]
	v_add3_u32 v0, s64, v226, v227
	v_add3_u32 v0, v0, v228, v229
	ds_write_b128 v0, v[66:69] offset:16384
	s_cselect_b64 s[0:1], -1, 0
	s_and_b64 s[0:1], s[12:13], s[0:1]
	s_cmp_ge_i32 s61, s63
	s_cselect_b64 s[16:17], -1, 0
	s_and_b64 s[0:1], s[0:1], s[16:17]
	s_andn2_b64 vcc, exec, s[0:1]
	s_waitcnt vmcnt(0)
	v_cvt_pk_bf16_f32 v86, v86, v87
	v_cvt_pk_bf16_f32 v87, v88, v89
	v_cvt_pk_bf16_f32 v88, v82, v83
	v_cvt_pk_bf16_f32 v89, v84, v85
	v_cvt_pk_bf16_f32 v82, v94, v95
	v_cvt_pk_bf16_f32 v83, v96, v97
	v_cvt_pk_bf16_f32 v84, v90, v91
	v_cvt_pk_bf16_f32 v85, v92, v93
	v_add3_u32 v0, s64, v232, v233
	ds_write_b128 v0, v[86:89]
	v_add3_u32 v0, s64, v234, v235
	v_add3_u32 v0, v0, v236, v237
	ds_write_b128 v0, v[82:85] offset:16384
	s_waitcnt lgkmcnt(0)
	s_barrier
	s_cbranch_vccnz .LBB0_446
	v_add3_u32 v0, s64, v194, v193
	ds_read_b128 v[126:129], v0
	ds_read_b128 v[118:121], v0 offset:8192
	v_add3_u32 v0, s64, v195, v193
	ds_read_b128 v[122:125], v0
	ds_read_b128 v[114:117], v0 offset:8192
	v_cvt_f32_i32_e32 v0, v238
	s_cmp_lt_u32 s61, s62
	s_mov_b64 s[0:1], -1
	s_cbranch_scc0 .LBB0_454
	s_andn2_b64 vcc, exec, s[0:1]
	s_cbranch_vccz .LBB0_455
